# grid barrier: non-leader workgroups poll the cross-XCD release generation directly (one release hop fewer per barrier), on top of v032
# speedup vs baseline: 1.0040x; 1.0040x over previous
; __device__ __forceinline__ unsigned xb_ld(unsigned* p)              { return __hip_atomic_load(p, __ATOMIC_RELAXED, __HIP_MEMORY_SCOPE_AGENT); }
; __device__ __forceinline__ unsigned xb_add(unsigned* p, unsigned v) { return __hip_atomic_fetch_add(p, v, __ATOMIC_RELAXED, __HIP_MEMORY_SCOPE_AGENT); }
; #define XB_SPIN(cond, bar) do { unsigned _sp = 0; while (cond) { __builtin_amdgcn_s_sleep(1); \
;     if ((++_sp & 255u) == 0u) { if (xb_ld(&(bar)[XB_TMO])) break; if (_sp > XB_SPIN_CAP) { atomicAdd(&(bar)[XB_TMO], 1u); break; } } } } while (0)
; __device__ __forceinline__ void xcd_barrier(const XcdBarrier& b) {
;     ...
;         unsigned nloc = b.st[0], nx = b.st[1];
;         if (nloc == 0u) { xcd_barrier_complete(bar, b.x, nloc, nx); b.st[0] = nloc; b.st[1] = nx; }
;         const unsigned old = xb_add(&bar[XB_XSUB(b.x)], 1u);
;         const unsigned gen = old / nloc;
;         if (old + 1u == (gen + 1u) * nloc) {
;             __builtin_amdgcn_fence(__ATOMIC_RELEASE, "agent");
;             asm volatile("s_waitcnt vmcnt(0)" ::: "memory");
;             const unsigned og = xb_add(&bar[XB_TOP], 1u);
;             const unsigned tg = og / nx;
;             if (og + 1u == (tg + 1u) * nx) xb_add(&bar[XB_TOPGEN], 1u);
;             else XB_SPIN(xb_ld(&bar[XB_TOPGEN]) == tg, bar);
;             __builtin_amdgcn_fence(__ATOMIC_ACQUIRE, "agent");
;             xb_add(&bar[XB_XGEN(b.x)], 1u);
;             asm volatile("s_waitcnt vmcnt(0)" ::: "memory");
;         } else {
;             XB_SPIN(xb_ld(&bar[XB_XGEN(b.x)]) == gen, bar);
.LBB0_59:
	s_or_b64 exec, exec, s[6:7]
	v_cvt_f32_u32_e32 v4, v2
	s_waitcnt vmcnt(0)
	v_readfirstlane_b32 s2, v3
	v_sub_u32_e32 v3, 0, v2
	v_rcp_iflag_f32_e32 v4, v4
	v_add_u32_e32 v5, s2, v1
	v_mul_f32_e32 v4, 0x4f7ffffe, v4
	v_cvt_u32_f32_e32 v4, v4
	v_mul_lo_u32 v1, v3, v4
	v_mul_hi_u32 v1, v4, v1
	v_add_u32_e32 v1, v4, v1
	v_mul_hi_u32 v1, v5, v1
	v_mul_lo_u32 v3, v1, v2
	v_sub_u32_e32 v3, v5, v3
	v_add_u32_e32 v4, 1, v1
	v_cmp_ge_u32_e32 vcc, v3, v2
	s_nop 1
	v_cndmask_b32_e32 v1, v1, v4, vcc
	v_sub_u32_e32 v4, v3, v2
	v_cndmask_b32_e32 v3, v3, v4, vcc
	v_add_u32_e32 v4, 1, v1
	v_cmp_ge_u32_e32 vcc, v3, v2
	v_add_u32_e32 v3, 1, v5
	s_nop 0
	v_cndmask_b32_e32 v1, v1, v4, vcc
	v_mul_lo_u32 v4, v2, v1
	v_add_u32_e32 v2, v4, v2
	v_cmp_ne_u32_e32 vcc, v3, v2
	s_and_saveexec_b64 s[2:3], vcc
	s_xor_b64 s[6:7], exec, s[2:3]
	s_cbranch_execz .LBB0_73
	v_readlane_b32 s2, v253, 57
	s_waitcnt lgkmcnt(0)
	v_mov_b32_e32 v0, 0
	v_readlane_b32 s3, v253, 58
	s_nop 4
	global_load_dword v2, v0, s[2:3] sc1
	s_waitcnt vmcnt(0)
	v_cmp_eq_u32_e32 vcc, v2, v1
	s_and_saveexec_b64 s[8:9], vcc
	s_cbranch_execz .LBB0_72
	s_mov_b32 s2, 1
	s_mov_b64 s[10:11], 0
	s_branch .LBB0_63

; __device__ __forceinline__ unsigned xb_ld(unsigned* p)              { return __hip_atomic_load(p, __ATOMIC_RELAXED, __HIP_MEMORY_SCOPE_AGENT); }
; #define XB_SPIN(cond, bar) do { unsigned _sp = 0; while (cond) { __builtin_amdgcn_s_sleep(1); \
;     if ((++_sp & 255u) == 0u) { if (xb_ld(&(bar)[XB_TMO])) break; if (_sp > XB_SPIN_CAP) { atomicAdd(&(bar)[XB_TMO], 1u); break; } } } } while (0)
; __device__ __forceinline__ void xcd_barrier(const XcdBarrier& b) {
;     ...
;             XB_SPIN(xb_ld(&bar[XB_XGEN(b.x)]) == gen, bar);
.LBB0_67:
	v_readlane_b32 s14, v253, 57
	v_readlane_b32 s15, v253, 58
	s_add_i32 s2, s2, 1
	s_mov_b64 s[16:17], -1
	s_nop 2
	global_load_dword v2, v0, s[14:15] sc1
	s_waitcnt vmcnt(0)
	v_cmp_ne_u32_e32 vcc, v2, v1
	s_orn2_b64 s[14:15], vcc, exec
	s_branch .LBB0_62

; __device__ __forceinline__ unsigned xb_ld(unsigned* p)              { return __hip_atomic_load(p, __ATOMIC_RELAXED, __HIP_MEMORY_SCOPE_AGENT); }
; __device__ __forceinline__ unsigned xb_add(unsigned* p, unsigned v) { return __hip_atomic_fetch_add(p, v, __ATOMIC_RELAXED, __HIP_MEMORY_SCOPE_AGENT); }
; #define XB_SPIN(cond, bar) do { unsigned _sp = 0; while (cond) { __builtin_amdgcn_s_sleep(1); \
;     if ((++_sp & 255u) == 0u) { if (xb_ld(&(bar)[XB_TMO])) break; if (_sp > XB_SPIN_CAP) { atomicAdd(&(bar)[XB_TMO], 1u); break; } } } } while (0)
; __device__ __forceinline__ void xcd_barrier(const XcdBarrier& b) {
;     ...
;         unsigned nloc = b.st[0], nx = b.st[1];
;         if (nloc == 0u) { xcd_barrier_complete(bar, b.x, nloc, nx); b.st[0] = nloc; b.st[1] = nx; }
;         const unsigned old = xb_add(&bar[XB_XSUB(b.x)], 1u);
;         const unsigned gen = old / nloc;
;         if (old + 1u == (gen + 1u) * nloc) {
;             __builtin_amdgcn_fence(__ATOMIC_RELEASE, "agent");
;             asm volatile("s_waitcnt vmcnt(0)" ::: "memory");
;             const unsigned og = xb_add(&bar[XB_TOP], 1u);
;             const unsigned tg = og / nx;
;             if (og + 1u == (tg + 1u) * nx) xb_add(&bar[XB_TOPGEN], 1u);
;             else XB_SPIN(xb_ld(&bar[XB_TOPGEN]) == tg, bar);
;             __builtin_amdgcn_fence(__ATOMIC_ACQUIRE, "agent");
;             xb_add(&bar[XB_XGEN(b.x)], 1u);
;             asm volatile("s_waitcnt vmcnt(0)" ::: "memory");
;         } else {
;             XB_SPIN(xb_ld(&bar[XB_XGEN(b.x)]) == gen, bar);
.LBB0_145:
	s_or_b64 exec, exec, s[14:15]
	v_cvt_f32_u32_e32 v5, v3
	s_waitcnt vmcnt(0)
	v_readfirstlane_b32 s14, v4
	v_sub_u32_e32 v4, 0, v3
	v_rcp_iflag_f32_e32 v5, v5
	v_add_u32_e32 v6, s14, v0
	v_mul_f32_e32 v5, 0x4f7ffffe, v5
	v_cvt_u32_f32_e32 v5, v5
	v_mul_lo_u32 v0, v4, v5
	v_mul_hi_u32 v0, v5, v0
	v_add_u32_e32 v0, v5, v0
	v_mul_hi_u32 v0, v6, v0
	v_mul_lo_u32 v4, v0, v3
	v_sub_u32_e32 v4, v6, v4
	v_add_u32_e32 v5, 1, v0
	v_cmp_ge_u32_e32 vcc, v4, v3
	s_nop 1
	v_cndmask_b32_e32 v0, v0, v5, vcc
	v_sub_u32_e32 v5, v4, v3
	v_cndmask_b32_e32 v4, v4, v5, vcc
	v_add_u32_e32 v5, 1, v0
	v_cmp_ge_u32_e32 vcc, v4, v3
	v_add_u32_e32 v4, 1, v6
	s_nop 0
	v_cndmask_b32_e32 v0, v0, v5, vcc
	v_mul_lo_u32 v5, v3, v0
	v_add_u32_e32 v3, v5, v3
	v_cmp_ne_u32_e32 vcc, v4, v3
	s_and_saveexec_b64 s[14:15], vcc
	s_xor_b64 s[14:15], exec, s[14:15]
	s_cbranch_execz .LBB0_159
	v_readlane_b32 s18, v253, 57
	v_readlane_b32 s19, v253, 58
	s_waitcnt lgkmcnt(0)
	s_nop 3
	global_load_dword v2, v1, s[18:19] sc1
	s_waitcnt vmcnt(0)
	v_cmp_eq_u32_e32 vcc, v2, v0
	s_and_saveexec_b64 s[28:29], vcc
	s_cbranch_execz .LBB0_158
	s_mov_b32 s18, 1
	s_mov_b64 s[38:39], 0
	s_branch .LBB0_149

; __device__ __forceinline__ unsigned xb_ld(unsigned* p)              { return __hip_atomic_load(p, __ATOMIC_RELAXED, __HIP_MEMORY_SCOPE_AGENT); }
; __device__ __forceinline__ unsigned xb_add(unsigned* p, unsigned v) { return __hip_atomic_fetch_add(p, v, __ATOMIC_RELAXED, __HIP_MEMORY_SCOPE_AGENT); }
; #define XB_SPIN(cond, bar) do { unsigned _sp = 0; while (cond) { __builtin_amdgcn_s_sleep(1); \
;     if ((++_sp & 255u) == 0u) { if (xb_ld(&(bar)[XB_TMO])) break; if (_sp > XB_SPIN_CAP) { atomicAdd(&(bar)[XB_TMO], 1u); break; } } } } while (0)
; __device__ __forceinline__ void xcd_barrier(const XcdBarrier& b) {
;     ...
;         unsigned nloc = b.st[0], nx = b.st[1];
;         if (nloc == 0u) { xcd_barrier_complete(bar, b.x, nloc, nx); b.st[0] = nloc; b.st[1] = nx; }
;         const unsigned old = xb_add(&bar[XB_XSUB(b.x)], 1u);
;         const unsigned gen = old / nloc;
;         if (old + 1u == (gen + 1u) * nloc) {
;             __builtin_amdgcn_fence(__ATOMIC_RELEASE, "agent");
;             asm volatile("s_waitcnt vmcnt(0)" ::: "memory");
;             const unsigned og = xb_add(&bar[XB_TOP], 1u);
;             const unsigned tg = og / nx;
;             if (og + 1u == (tg + 1u) * nx) xb_add(&bar[XB_TOPGEN], 1u);
;             else XB_SPIN(xb_ld(&bar[XB_TOPGEN]) == tg, bar);
;             __builtin_amdgcn_fence(__ATOMIC_ACQUIRE, "agent");
;             xb_add(&bar[XB_XGEN(b.x)], 1u);
;             asm volatile("s_waitcnt vmcnt(0)" ::: "memory");
;         } else {
;             XB_SPIN(xb_ld(&bar[XB_XGEN(b.x)]) == gen, bar);
.LBB0_577:
	s_or_b64 exec, exec, s[14:15]
	v_cvt_f32_u32_e32 v5, v3
	s_waitcnt vmcnt(0)
	v_readfirstlane_b32 s14, v4
	v_sub_u32_e32 v4, 0, v3
	v_rcp_iflag_f32_e32 v5, v5
	v_add_u32_e32 v6, s14, v0
	v_mul_f32_e32 v5, 0x4f7ffffe, v5
	v_cvt_u32_f32_e32 v5, v5
	v_mul_lo_u32 v0, v4, v5
	v_mul_hi_u32 v0, v5, v0
	v_add_u32_e32 v0, v5, v0
	v_mul_hi_u32 v0, v6, v0
	v_mul_lo_u32 v4, v0, v3
	v_sub_u32_e32 v4, v6, v4
	v_add_u32_e32 v5, 1, v0
	v_cmp_ge_u32_e32 vcc, v4, v3
	s_nop 1
	v_cndmask_b32_e32 v0, v0, v5, vcc
	v_sub_u32_e32 v5, v4, v3
	v_cndmask_b32_e32 v4, v4, v5, vcc
	v_add_u32_e32 v5, 1, v0
	v_cmp_ge_u32_e32 vcc, v4, v3
	v_add_u32_e32 v4, 1, v6
	s_nop 0
	v_cndmask_b32_e32 v0, v0, v5, vcc
	v_mul_lo_u32 v5, v3, v0
	v_add_u32_e32 v3, v5, v3
	v_cmp_ne_u32_e32 vcc, v4, v3
	s_and_saveexec_b64 s[14:15], vcc
	s_xor_b64 s[14:15], exec, s[14:15]
	s_cbranch_execz .LBB0_591
	v_readlane_b32 s18, v253, 57
	v_readlane_b32 s19, v253, 58
	s_waitcnt lgkmcnt(0)
	s_nop 3
	global_load_dword v2, v1, s[18:19] sc1
	s_waitcnt vmcnt(0)
	v_cmp_eq_u32_e32 vcc, v2, v0
	s_and_saveexec_b64 s[28:29], vcc
	s_cbranch_execz .LBB0_590
	s_mov_b32 s18, 1
	s_mov_b64 s[34:35], 0
	s_branch .LBB0_581
